# norm_rows PA/PS LDS fill (P1,P8): 32 serial load-wait-write iterations unrolled, invariants loaded once, mod rows double-buffered
# speedup vs baseline: 1.0040x; 1.0028x over previous
.LBB0_91:
	s_cmp_lt_i32 s70, 2
	s_cselect_b64 s[2:3], -1, 0
	s_add_u32 s54, s68, 0x11000000
	s_addc_u32 s55, s69, 0
	s_and_b64 s[0:1], s[2:3], s[0:1]
	s_andn2_b64 vcc, exec, s[0:1]
	s_cbranch_vccnz .LBB0_104
	v_readlane_b32 s6, v254, 24
	v_readlane_b32 s7, v254, 25
	v_lshl_add_u32 v1, v0, 2, 0
	s_mov_b64 s[2:3], 0
	v_mov_b32_e32 v3, 0
	s_mov_b32 s4, 0xc000
	v_mov_b64_e32 v[4:5], s[6:7]
	s_movk_i32 s5, 0x3dff
	v_mov_b32_e32 v6, v0
	s_barrier
	v_mov_b32_e32 v14, v1
	v_add_u32_e32 v15, 0x1000, v1
	v_add_u32_e32 v16, 0x2000, v1
	v_add_u32_e32 v17, 0x3000, v1
	v_add_u32_e32 v18, 0x4000, v14
	v_add_u32_e32 v19, 0x4000, v15
	v_add_u32_e32 v20, 0x4000, v16
	v_add_u32_e32 v21, 0x4000, v17
	v_add_u32_e32 v22, 0x10000, v1
	global_load_dword v24, v14, s[52:53]
	global_load_dword v32, v14, s[56:57]
	global_load_dword v40, v18, s[56:57]
	global_load_dword v25, v14, s[52:53] offset:2048
	global_load_dword v33, v14, s[56:57] offset:2048
	global_load_dword v41, v18, s[56:57] offset:2048
	global_load_dword v26, v15, s[52:53]
	global_load_dword v34, v15, s[56:57]
	global_load_dword v42, v19, s[56:57]
	global_load_dword v27, v15, s[52:53] offset:2048
	global_load_dword v35, v15, s[56:57] offset:2048
	global_load_dword v43, v19, s[56:57] offset:2048
	global_load_dword v28, v16, s[52:53]
	global_load_dword v36, v16, s[56:57]
	global_load_dword v44, v20, s[56:57]
	global_load_dword v29, v16, s[52:53] offset:2048
	global_load_dword v37, v16, s[56:57] offset:2048
	global_load_dword v45, v20, s[56:57] offset:2048
	global_load_dword v30, v17, s[52:53]
	global_load_dword v38, v17, s[56:57]
	global_load_dword v46, v21, s[56:57]
	global_load_dword v31, v17, s[52:53] offset:2048
	global_load_dword v39, v17, s[56:57] offset:2048
	global_load_dword v47, v21, s[56:57] offset:2048
	s_mov_b32 s98, s6
	s_mov_b32 s99, s7
	global_load_dword v48, v18, s[98:99]
	global_load_dword v56, v14, s[98:99]
	global_load_dword v49, v18, s[98:99] offset:2048
	global_load_dword v57, v14, s[98:99] offset:2048
	global_load_dword v50, v19, s[98:99]
	global_load_dword v58, v15, s[98:99]
	global_load_dword v51, v19, s[98:99] offset:2048
	global_load_dword v59, v15, s[98:99] offset:2048
	global_load_dword v52, v20, s[98:99]
	global_load_dword v60, v16, s[98:99]
	global_load_dword v53, v20, s[98:99] offset:2048
	global_load_dword v61, v16, s[98:99] offset:2048
	global_load_dword v54, v21, s[98:99]
	global_load_dword v62, v17, s[98:99]
	global_load_dword v55, v21, s[98:99] offset:2048
	global_load_dword v63, v17, s[98:99] offset:2048
	s_add_u32 s98, s6, 0xc000
	s_addc_u32 s99, s7, 0
	global_load_dword v64, v18, s[98:99]
	global_load_dword v72, v14, s[98:99]
	global_load_dword v65, v18, s[98:99] offset:2048
	global_load_dword v73, v14, s[98:99] offset:2048
	global_load_dword v66, v19, s[98:99]
	global_load_dword v74, v15, s[98:99]
	global_load_dword v67, v19, s[98:99] offset:2048
	global_load_dword v75, v15, s[98:99] offset:2048
	global_load_dword v68, v20, s[98:99]
	global_load_dword v76, v16, s[98:99]
	global_load_dword v69, v20, s[98:99] offset:2048
	global_load_dword v77, v16, s[98:99] offset:2048
	global_load_dword v70, v21, s[98:99]
	global_load_dword v78, v17, s[98:99]
	global_load_dword v71, v21, s[98:99] offset:2048
	global_load_dword v79, v17, s[98:99] offset:2048
	s_waitcnt vmcnt(16)
	v_add_f32_e32 v80, 1.0, v48
	v_add_f32_e32 v80, v80, v40
	v_mul_f32_e32 v80, v24, v80
	v_add_f32_e32 v81, v56, v32
	ds_write_b32 v1, v80
	ds_write_b32 v22, v81
	v_add_f32_e32 v80, 1.0, v49
	v_add_f32_e32 v80, v80, v41
	v_mul_f32_e32 v80, v25, v80
	v_add_f32_e32 v81, v57, v33
	ds_write_b32 v1, v80 offset:2048
	ds_write_b32 v22, v81 offset:2048
	v_add_f32_e32 v80, 1.0, v50
	v_add_f32_e32 v80, v80, v42
	v_mul_f32_e32 v80, v26, v80
	v_add_f32_e32 v81, v58, v34
	ds_write_b32 v1, v80 offset:4096
	ds_write_b32 v22, v81 offset:4096
	v_add_f32_e32 v80, 1.0, v51
	v_add_f32_e32 v80, v80, v43
	v_mul_f32_e32 v80, v27, v80
	v_add_f32_e32 v81, v59, v35
	ds_write_b32 v1, v80 offset:6144
	ds_write_b32 v22, v81 offset:6144
	v_add_f32_e32 v80, 1.0, v52
	v_add_f32_e32 v80, v80, v44
	v_mul_f32_e32 v80, v28, v80
	v_add_f32_e32 v81, v60, v36
	ds_write_b32 v1, v80 offset:8192
	ds_write_b32 v22, v81 offset:8192
	v_add_f32_e32 v80, 1.0, v53
	v_add_f32_e32 v80, v80, v45
	v_mul_f32_e32 v80, v29, v80
	v_add_f32_e32 v81, v61, v37
	ds_write_b32 v1, v80 offset:10240
	ds_write_b32 v22, v81 offset:10240
	v_add_f32_e32 v80, 1.0, v54
	v_add_f32_e32 v80, v80, v46
	v_mul_f32_e32 v80, v30, v80
	v_add_f32_e32 v81, v62, v38
	ds_write_b32 v1, v80 offset:12288
	ds_write_b32 v22, v81 offset:12288
	v_add_f32_e32 v80, 1.0, v55
	v_add_f32_e32 v80, v80, v47
	v_mul_f32_e32 v80, v31, v80
	v_add_f32_e32 v81, v63, v39
	ds_write_b32 v1, v80 offset:14336
	ds_write_b32 v22, v81 offset:14336
	s_add_u32 s98, s6, 0x18000
	s_addc_u32 s99, s7, 0
	global_load_dword v48, v18, s[98:99]
	global_load_dword v56, v14, s[98:99]
	global_load_dword v49, v18, s[98:99] offset:2048
	global_load_dword v57, v14, s[98:99] offset:2048
	global_load_dword v50, v19, s[98:99]
	global_load_dword v58, v15, s[98:99]
	global_load_dword v51, v19, s[98:99] offset:2048
	global_load_dword v59, v15, s[98:99] offset:2048
	global_load_dword v52, v20, s[98:99]
	global_load_dword v60, v16, s[98:99]
	global_load_dword v53, v20, s[98:99] offset:2048
	global_load_dword v61, v16, s[98:99] offset:2048
	global_load_dword v54, v21, s[98:99]
	global_load_dword v62, v17, s[98:99]
	global_load_dword v55, v21, s[98:99] offset:2048
	global_load_dword v63, v17, s[98:99] offset:2048
	s_waitcnt vmcnt(16)
	v_add_f32_e32 v80, 1.0, v64
	v_add_f32_e32 v80, v80, v40
	v_mul_f32_e32 v80, v24, v80
	v_add_f32_e32 v81, v72, v32
	ds_write_b32 v1, v80 offset:16384
	ds_write_b32 v22, v81 offset:16384
	v_add_f32_e32 v80, 1.0, v65
	v_add_f32_e32 v80, v80, v41
	v_mul_f32_e32 v80, v25, v80
	v_add_f32_e32 v81, v73, v33
	ds_write_b32 v1, v80 offset:18432
	ds_write_b32 v22, v81 offset:18432
	v_add_f32_e32 v80, 1.0, v66
	v_add_f32_e32 v80, v80, v42
	v_mul_f32_e32 v80, v26, v80
	v_add_f32_e32 v81, v74, v34
	ds_write_b32 v1, v80 offset:20480
	ds_write_b32 v22, v81 offset:20480
	v_add_f32_e32 v80, 1.0, v67
	v_add_f32_e32 v80, v80, v43
	v_mul_f32_e32 v80, v27, v80
	v_add_f32_e32 v81, v75, v35
	ds_write_b32 v1, v80 offset:22528
	ds_write_b32 v22, v81 offset:22528
	v_add_f32_e32 v80, 1.0, v68
	v_add_f32_e32 v80, v80, v44
	v_mul_f32_e32 v80, v28, v80
	v_add_f32_e32 v81, v76, v36
	ds_write_b32 v1, v80 offset:24576
	ds_write_b32 v22, v81 offset:24576
	v_add_f32_e32 v80, 1.0, v69
	v_add_f32_e32 v80, v80, v45
	v_mul_f32_e32 v80, v29, v80
	v_add_f32_e32 v81, v77, v37
	ds_write_b32 v1, v80 offset:26624
	ds_write_b32 v22, v81 offset:26624
	v_add_f32_e32 v80, 1.0, v70
	v_add_f32_e32 v80, v80, v46
	v_mul_f32_e32 v80, v30, v80
	v_add_f32_e32 v81, v78, v38
	ds_write_b32 v1, v80 offset:28672
	ds_write_b32 v22, v81 offset:28672
	v_add_f32_e32 v80, 1.0, v71
	v_add_f32_e32 v80, v80, v47
	v_mul_f32_e32 v80, v31, v80
	v_add_f32_e32 v81, v79, v39
	ds_write_b32 v1, v80 offset:30720
	ds_write_b32 v22, v81 offset:30720
	s_add_u32 s98, s6, 0x24000
	s_addc_u32 s99, s7, 0
	global_load_dword v64, v18, s[98:99]
	global_load_dword v72, v14, s[98:99]
	global_load_dword v65, v18, s[98:99] offset:2048
	global_load_dword v73, v14, s[98:99] offset:2048
	global_load_dword v66, v19, s[98:99]
	global_load_dword v74, v15, s[98:99]
	global_load_dword v67, v19, s[98:99] offset:2048
	global_load_dword v75, v15, s[98:99] offset:2048
	global_load_dword v68, v20, s[98:99]
	global_load_dword v76, v16, s[98:99]
	global_load_dword v69, v20, s[98:99] offset:2048
	global_load_dword v77, v16, s[98:99] offset:2048
	global_load_dword v70, v21, s[98:99]
	global_load_dword v78, v17, s[98:99]
	global_load_dword v71, v21, s[98:99] offset:2048
	global_load_dword v79, v17, s[98:99] offset:2048
	s_waitcnt vmcnt(16)
	v_add_f32_e32 v80, 1.0, v48
	v_add_f32_e32 v80, v80, v40
	v_mul_f32_e32 v80, v24, v80
	v_add_f32_e32 v81, v56, v32
	ds_write_b32 v1, v80 offset:32768
	ds_write_b32 v22, v81 offset:32768
	v_add_f32_e32 v80, 1.0, v49
	v_add_f32_e32 v80, v80, v41
	v_mul_f32_e32 v80, v25, v80
	v_add_f32_e32 v81, v57, v33
	ds_write_b32 v1, v80 offset:34816
	ds_write_b32 v22, v81 offset:34816
	v_add_f32_e32 v80, 1.0, v50
	v_add_f32_e32 v80, v80, v42
	v_mul_f32_e32 v80, v26, v80
	v_add_f32_e32 v81, v58, v34
	ds_write_b32 v1, v80 offset:36864
	ds_write_b32 v22, v81 offset:36864
	v_add_f32_e32 v80, 1.0, v51
	v_add_f32_e32 v80, v80, v43
	v_mul_f32_e32 v80, v27, v80
	v_add_f32_e32 v81, v59, v35
	ds_write_b32 v1, v80 offset:38912
	ds_write_b32 v22, v81 offset:38912
	v_add_f32_e32 v80, 1.0, v52
	v_add_f32_e32 v80, v80, v44
	v_mul_f32_e32 v80, v28, v80
	v_add_f32_e32 v81, v60, v36
	ds_write_b32 v1, v80 offset:40960
	ds_write_b32 v22, v81 offset:40960
	v_add_f32_e32 v80, 1.0, v53
	v_add_f32_e32 v80, v80, v45
	v_mul_f32_e32 v80, v29, v80
	v_add_f32_e32 v81, v61, v37
	ds_write_b32 v1, v80 offset:43008
	ds_write_b32 v22, v81 offset:43008
	v_add_f32_e32 v80, 1.0, v54
	v_add_f32_e32 v80, v80, v46
	v_mul_f32_e32 v80, v30, v80
	v_add_f32_e32 v81, v62, v38
	ds_write_b32 v1, v80 offset:45056
	ds_write_b32 v22, v81 offset:45056
	v_add_f32_e32 v80, 1.0, v55
	v_add_f32_e32 v80, v80, v47
	v_mul_f32_e32 v80, v31, v80
	v_add_f32_e32 v81, v63, v39
	ds_write_b32 v1, v80 offset:47104
	ds_write_b32 v22, v81 offset:47104
	s_waitcnt vmcnt(0)
	v_add_f32_e32 v80, 1.0, v64
	v_add_f32_e32 v80, v80, v40
	v_mul_f32_e32 v80, v24, v80
	v_add_f32_e32 v81, v72, v32
	ds_write_b32 v1, v80 offset:49152
	ds_write_b32 v22, v81 offset:49152
	v_add_f32_e32 v80, 1.0, v65
	v_add_f32_e32 v80, v80, v41
	v_mul_f32_e32 v80, v25, v80
	v_add_f32_e32 v81, v73, v33
	ds_write_b32 v1, v80 offset:51200
	ds_write_b32 v22, v81 offset:51200
	v_add_f32_e32 v80, 1.0, v66
	v_add_f32_e32 v80, v80, v42
	v_mul_f32_e32 v80, v26, v80
	v_add_f32_e32 v81, v74, v34
	ds_write_b32 v1, v80 offset:53248
	ds_write_b32 v22, v81 offset:53248
	v_add_f32_e32 v80, 1.0, v67
	v_add_f32_e32 v80, v80, v43
	v_mul_f32_e32 v80, v27, v80
	v_add_f32_e32 v81, v75, v35
	ds_write_b32 v1, v80 offset:55296
	ds_write_b32 v22, v81 offset:55296
	v_add_f32_e32 v80, 1.0, v68
	v_add_f32_e32 v80, v80, v44
	v_mul_f32_e32 v80, v28, v80
	v_add_f32_e32 v81, v76, v36
	ds_write_b32 v1, v80 offset:57344
	ds_write_b32 v22, v81 offset:57344
	v_add_f32_e32 v80, 1.0, v69
	v_add_f32_e32 v80, v80, v45
	v_mul_f32_e32 v80, v29, v80
	v_add_f32_e32 v81, v77, v37
	ds_write_b32 v1, v80 offset:59392
	ds_write_b32 v22, v81 offset:59392
	v_add_f32_e32 v80, 1.0, v70
	v_add_f32_e32 v80, v80, v46
	v_mul_f32_e32 v80, v30, v80
	v_add_f32_e32 v81, v78, v38
	ds_write_b32 v1, v80 offset:61440
	ds_write_b32 v22, v81 offset:61440
	v_add_f32_e32 v80, 1.0, v71
	v_add_f32_e32 v80, v80, v47
	v_mul_f32_e32 v80, v31, v80
	v_add_f32_e32 v81, v79, v39
	ds_write_b32 v1, v80 offset:63488
	ds_write_b32 v22, v81 offset:63488
	s_or_b64 exec, exec, s[2:3]
	s_lshl_b32 s2, s94, 3
	v_readlane_b32 s3, v254, 23
	s_add_i32 s2, s3, s2
	s_cmpk_gt_i32 s2, 0x3fff
	s_waitcnt lgkmcnt(0)
	s_barrier
	s_cbranch_scc1 .LBB0_103
	s_ashr_i32 s3, s2, 31
	s_lshl_b32 s4, s33, 4
	s_lshl_b32 s26, s33, 3
	s_lshl_b64 s[6:7], s[2:3], 14
	s_add_u32 s18, s48, s6
	s_addc_u32 s19, s49, s7
	v_mov_b32_e32 v131, 0
	v_lshlrev_b32_e32 v130, 5, v163
	v_lshl_add_u64 v[18:19], s[18:19], 0, v[130:131]
	s_movk_i32 s27, 0x1000
	v_add_co_u32_e32 v32, vcc, s27, v18
	s_movk_i32 s28, 0x2000
	s_nop 0
	v_addc_co_u32_e32 v33, vcc, 0, v19, vcc
	s_mov_b64 s[14:15], 0x1800
	s_mov_b64 s[16:17], 0x1000
	v_add_co_u32_e32 v34, vcc, s28, v18
	s_mov_b64 s[10:11], 0x2800
	s_mov_b64 s[12:13], 0x2000
	v_lshl_add_u64 v[22:23], v[18:19], 0, s[14:15]
	v_lshl_add_u64 v[14:15], v[18:19], 0, s[16:17]
	v_addc_co_u32_e32 v35, vcc, 0, v19, vcc
	v_lshl_add_u64 v[20:21], v[18:19], 0, s[10:11]
	v_lshl_add_u64 v[30:31], v[18:19], 0, s[12:13]
	global_load_dwordx4 v[2:5], v130, s[18:19] offset:16
	global_load_dwordx4 v[6:9], v130, s[18:19] offset:2048
	global_load_dwordx4 v[10:13], v130, s[18:19] offset:2064
	global_load_dwordx4 v[38:41], v[34:35], off offset:-4096
	s_nop 0
	global_load_dwordx4 v[14:17], v[14:15], off offset:16
	s_nop 0
	global_load_dwordx4 v[22:25], v[22:23], off offset:16
	s_nop 0
	global_load_dwordx4 v[26:29], v[34:35], off
	global_load_dwordx4 v[42:45], v[34:35], off offset:2048
	s_nop 0
	global_load_dwordx4 v[34:37], v[30:31], off offset:16
	global_load_dwordx4 v[46:49], v[20:21], off offset:16
	s_movk_i32 s5, 0x3000
	s_mov_b64 s[6:7], 0x3800
	s_mov_b64 s[8:9], 0x3000
	v_add_co_u32_e32 v58, vcc, s5, v18
	v_lshl_add_u64 v[54:55], v[18:19], 0, s[6:7]
	v_lshl_add_u64 v[56:57], v[18:19], 0, s[8:9]
	v_addc_co_u32_e32 v59, vcc, 0, v19, vcc
	global_load_dwordx4 v[30:33], v[32:33], off offset:2048
	s_nop 0
	global_load_dwordx4 v[50:53], v[58:59], off
	global_load_dwordx4 v[18:21], v130, s[18:19]
	global_load_dwordx4 v[62:65], v[58:59], off offset:2048
	global_load_dwordx4 v[78:81], v[56:57], off offset:16
	global_load_dwordx4 v[90:93], v[54:55], off offset:16
	v_mbcnt_lo_u32_b32 v1, -1, 0
	v_mbcnt_hi_u32_b32 v54, -1, v1
	v_and_b32_e32 v1, 64, v54
	v_add_u32_e32 v55, 64, v1
	v_xor_b32_e32 v1, 1, v54
	v_cmp_lt_i32_e32 vcc, v1, v55
	v_xor_b32_e32 v56, 2, v54
	s_lshl_b64 s[18:19], s[2:3], 13
	v_cndmask_b32_e32 v1, v54, v1, vcc
	v_cmp_lt_i32_e32 vcc, v56, v55
	s_add_u32 s18, s68, s18
	v_lshl_add_u64 v[132:133], s[48:49], 0, v[130:131]
	v_cndmask_b32_e32 v56, v54, v56, vcc
	v_lshlrev_b32_e32 v137, 2, v56
	v_xor_b32_e32 v56, 4, v54
	v_cmp_lt_i32_e32 vcc, v56, v55
	v_lshlrev_b32_e32 v130, 4, v163
	s_addc_u32 s19, s69, s19
	v_cndmask_b32_e32 v56, v54, v56, vcc
	v_lshlrev_b32_e32 v138, 2, v56
	v_xor_b32_e32 v56, 8, v54
	v_cmp_lt_i32_e32 vcc, v56, v55
	s_ashr_i32 s5, s4, 31
	v_lshlrev_b32_e32 v1, 2, v1
	v_cndmask_b32_e32 v56, v54, v56, vcc
	v_lshlrev_b32_e32 v139, 2, v56
	v_xor_b32_e32 v56, 16, v54
	v_cmp_lt_i32_e32 vcc, v56, v55
	v_mov_b32_e32 v142, 0x358637bd
	v_lshlrev_b32_e32 v136, 3, v163
	v_cndmask_b32_e32 v56, v54, v56, vcc
	v_lshlrev_b32_e32 v140, 2, v56
	v_xor_b32_e32 v56, 32, v54
	v_cmp_lt_i32_e32 vcc, v56, v55
	s_nop 1
	v_cndmask_b32_e32 v54, v54, v56, vcc
	v_lshlrev_b32_e32 v141, 2, v54
	v_lshl_add_u64 v[54:55], s[18:19], 0, v[130:131]
	s_mov_b64 s[18:19], 0x11000000
	v_lshl_add_u64 v[134:135], v[54:55], 0, s[18:19]
	s_lshl_b64 s[18:19], s[4:5], 13
	s_mov_b32 s5, 0x800000
	s_branch .LBB0_97

.LBB0_836:
	v_readlane_b32 s36, v254, 7
	v_readlane_b32 s46, v254, 17
	v_readlane_b32 s47, v254, 18
	v_readlane_b32 s50, v254, 21
	v_readlane_b32 s51, v254, 22
	s_mov_b64 s[6:7], 0
	s_waitcnt vmcnt(0)
	v_mov_b32_e32 v3, 0
	s_mov_b32 s5, 0xc000
	v_mov_b64_e32 v[4:5], s[2:3]
	s_movk_i32 s8, 0x3dff
	v_mov_b32_e32 v1, v0
	s_mov_b64 s[22:23], s[46:47]
	s_mov_b64 s[26:27], s[50:51]
	s_barrier
	v_readlane_b32 s37, v254, 8
	v_readlane_b32 s38, v254, 9
	v_readlane_b32 s39, v254, 10
	v_readlane_b32 s40, v254, 11
	v_readlane_b32 s41, v254, 12
	v_readlane_b32 s42, v254, 13
	v_readlane_b32 s43, v254, 14
	v_readlane_b32 s44, v254, 15
	v_readlane_b32 s45, v254, 16
	v_readlane_b32 s48, v254, 19
	v_readlane_b32 s49, v254, 20
	v_mov_b32_e32 v14, v183
	v_add_u32_e32 v15, 0x1000, v183
	v_add_u32_e32 v16, 0x2000, v183
	v_add_u32_e32 v17, 0x3000, v183
	v_add_u32_e32 v18, 0x4000, v14
	v_add_u32_e32 v19, 0x4000, v15
	v_add_u32_e32 v20, 0x4000, v16
	v_add_u32_e32 v21, 0x4000, v17
	v_add_u32_e32 v22, 0x10000, v183
	global_load_dword v24, v14, s[22:23]
	global_load_dword v32, v14, s[26:27]
	global_load_dword v40, v18, s[26:27]
	global_load_dword v25, v14, s[22:23] offset:2048
	global_load_dword v33, v14, s[26:27] offset:2048
	global_load_dword v41, v18, s[26:27] offset:2048
	global_load_dword v26, v15, s[22:23]
	global_load_dword v34, v15, s[26:27]
	global_load_dword v42, v19, s[26:27]
	global_load_dword v27, v15, s[22:23] offset:2048
	global_load_dword v35, v15, s[26:27] offset:2048
	global_load_dword v43, v19, s[26:27] offset:2048
	global_load_dword v28, v16, s[22:23]
	global_load_dword v36, v16, s[26:27]
	global_load_dword v44, v20, s[26:27]
	global_load_dword v29, v16, s[22:23] offset:2048
	global_load_dword v37, v16, s[26:27] offset:2048
	global_load_dword v45, v20, s[26:27] offset:2048
	global_load_dword v30, v17, s[22:23]
	global_load_dword v38, v17, s[26:27]
	global_load_dword v46, v21, s[26:27]
	global_load_dword v31, v17, s[22:23] offset:2048
	global_load_dword v39, v17, s[26:27] offset:2048
	global_load_dword v47, v21, s[26:27] offset:2048
	s_mov_b32 s98, s2
	s_mov_b32 s99, s3
	global_load_dword v48, v18, s[98:99]
	global_load_dword v56, v14, s[98:99]
	global_load_dword v49, v18, s[98:99] offset:2048
	global_load_dword v57, v14, s[98:99] offset:2048
	global_load_dword v50, v19, s[98:99]
	global_load_dword v58, v15, s[98:99]
	global_load_dword v51, v19, s[98:99] offset:2048
	global_load_dword v59, v15, s[98:99] offset:2048
	global_load_dword v52, v20, s[98:99]
	global_load_dword v60, v16, s[98:99]
	global_load_dword v53, v20, s[98:99] offset:2048
	global_load_dword v61, v16, s[98:99] offset:2048
	global_load_dword v54, v21, s[98:99]
	global_load_dword v62, v17, s[98:99]
	global_load_dword v55, v21, s[98:99] offset:2048
	global_load_dword v63, v17, s[98:99] offset:2048
	s_add_u32 s98, s2, 0xc000
	s_addc_u32 s99, s3, 0
	global_load_dword v64, v18, s[98:99]
	global_load_dword v72, v14, s[98:99]
	global_load_dword v65, v18, s[98:99] offset:2048
	global_load_dword v73, v14, s[98:99] offset:2048
	global_load_dword v66, v19, s[98:99]
	global_load_dword v74, v15, s[98:99]
	global_load_dword v67, v19, s[98:99] offset:2048
	global_load_dword v75, v15, s[98:99] offset:2048
	global_load_dword v68, v20, s[98:99]
	global_load_dword v76, v16, s[98:99]
	global_load_dword v69, v20, s[98:99] offset:2048
	global_load_dword v77, v16, s[98:99] offset:2048
	global_load_dword v70, v21, s[98:99]
	global_load_dword v78, v17, s[98:99]
	global_load_dword v71, v21, s[98:99] offset:2048
	global_load_dword v79, v17, s[98:99] offset:2048
	s_waitcnt vmcnt(16)
	v_add_f32_e32 v80, 1.0, v48
	v_add_f32_e32 v80, v80, v40
	v_mul_f32_e32 v80, v24, v80
	v_add_f32_e32 v81, v56, v32
	ds_write_b32 v183, v80
	ds_write_b32 v22, v81
	v_add_f32_e32 v80, 1.0, v49
	v_add_f32_e32 v80, v80, v41
	v_mul_f32_e32 v80, v25, v80
	v_add_f32_e32 v81, v57, v33
	ds_write_b32 v183, v80 offset:2048
	ds_write_b32 v22, v81 offset:2048
	v_add_f32_e32 v80, 1.0, v50
	v_add_f32_e32 v80, v80, v42
	v_mul_f32_e32 v80, v26, v80
	v_add_f32_e32 v81, v58, v34
	ds_write_b32 v183, v80 offset:4096
	ds_write_b32 v22, v81 offset:4096
	v_add_f32_e32 v80, 1.0, v51
	v_add_f32_e32 v80, v80, v43
	v_mul_f32_e32 v80, v27, v80
	v_add_f32_e32 v81, v59, v35
	ds_write_b32 v183, v80 offset:6144
	ds_write_b32 v22, v81 offset:6144
	v_add_f32_e32 v80, 1.0, v52
	v_add_f32_e32 v80, v80, v44
	v_mul_f32_e32 v80, v28, v80
	v_add_f32_e32 v81, v60, v36
	ds_write_b32 v183, v80 offset:8192
	ds_write_b32 v22, v81 offset:8192
	v_add_f32_e32 v80, 1.0, v53
	v_add_f32_e32 v80, v80, v45
	v_mul_f32_e32 v80, v29, v80
	v_add_f32_e32 v81, v61, v37
	ds_write_b32 v183, v80 offset:10240
	ds_write_b32 v22, v81 offset:10240
	v_add_f32_e32 v80, 1.0, v54
	v_add_f32_e32 v80, v80, v46
	v_mul_f32_e32 v80, v30, v80
	v_add_f32_e32 v81, v62, v38
	ds_write_b32 v183, v80 offset:12288
	ds_write_b32 v22, v81 offset:12288
	v_add_f32_e32 v80, 1.0, v55
	v_add_f32_e32 v80, v80, v47
	v_mul_f32_e32 v80, v31, v80
	v_add_f32_e32 v81, v63, v39
	ds_write_b32 v183, v80 offset:14336
	ds_write_b32 v22, v81 offset:14336
	s_add_u32 s98, s2, 0x18000
	s_addc_u32 s99, s3, 0
	global_load_dword v48, v18, s[98:99]
	global_load_dword v56, v14, s[98:99]
	global_load_dword v49, v18, s[98:99] offset:2048
	global_load_dword v57, v14, s[98:99] offset:2048
	global_load_dword v50, v19, s[98:99]
	global_load_dword v58, v15, s[98:99]
	global_load_dword v51, v19, s[98:99] offset:2048
	global_load_dword v59, v15, s[98:99] offset:2048
	global_load_dword v52, v20, s[98:99]
	global_load_dword v60, v16, s[98:99]
	global_load_dword v53, v20, s[98:99] offset:2048
	global_load_dword v61, v16, s[98:99] offset:2048
	global_load_dword v54, v21, s[98:99]
	global_load_dword v62, v17, s[98:99]
	global_load_dword v55, v21, s[98:99] offset:2048
	global_load_dword v63, v17, s[98:99] offset:2048
	s_waitcnt vmcnt(16)
	v_add_f32_e32 v80, 1.0, v64
	v_add_f32_e32 v80, v80, v40
	v_mul_f32_e32 v80, v24, v80
	v_add_f32_e32 v81, v72, v32
	ds_write_b32 v183, v80 offset:16384
	ds_write_b32 v22, v81 offset:16384
	v_add_f32_e32 v80, 1.0, v65
	v_add_f32_e32 v80, v80, v41
	v_mul_f32_e32 v80, v25, v80
	v_add_f32_e32 v81, v73, v33
	ds_write_b32 v183, v80 offset:18432
	ds_write_b32 v22, v81 offset:18432
	v_add_f32_e32 v80, 1.0, v66
	v_add_f32_e32 v80, v80, v42
	v_mul_f32_e32 v80, v26, v80
	v_add_f32_e32 v81, v74, v34
	ds_write_b32 v183, v80 offset:20480
	ds_write_b32 v22, v81 offset:20480
	v_add_f32_e32 v80, 1.0, v67
	v_add_f32_e32 v80, v80, v43
	v_mul_f32_e32 v80, v27, v80
	v_add_f32_e32 v81, v75, v35
	ds_write_b32 v183, v80 offset:22528
	ds_write_b32 v22, v81 offset:22528
	v_add_f32_e32 v80, 1.0, v68
	v_add_f32_e32 v80, v80, v44
	v_mul_f32_e32 v80, v28, v80
	v_add_f32_e32 v81, v76, v36
	ds_write_b32 v183, v80 offset:24576
	ds_write_b32 v22, v81 offset:24576
	v_add_f32_e32 v80, 1.0, v69
	v_add_f32_e32 v80, v80, v45
	v_mul_f32_e32 v80, v29, v80
	v_add_f32_e32 v81, v77, v37
	ds_write_b32 v183, v80 offset:26624
	ds_write_b32 v22, v81 offset:26624
	v_add_f32_e32 v80, 1.0, v70
	v_add_f32_e32 v80, v80, v46
	v_mul_f32_e32 v80, v30, v80
	v_add_f32_e32 v81, v78, v38
	ds_write_b32 v183, v80 offset:28672
	ds_write_b32 v22, v81 offset:28672
	v_add_f32_e32 v80, 1.0, v71
	v_add_f32_e32 v80, v80, v47
	v_mul_f32_e32 v80, v31, v80
	v_add_f32_e32 v81, v79, v39
	ds_write_b32 v183, v80 offset:30720
	ds_write_b32 v22, v81 offset:30720
	s_add_u32 s98, s2, 0x24000
	s_addc_u32 s99, s3, 0
	global_load_dword v64, v18, s[98:99]
	global_load_dword v72, v14, s[98:99]
	global_load_dword v65, v18, s[98:99] offset:2048
	global_load_dword v73, v14, s[98:99] offset:2048
	global_load_dword v66, v19, s[98:99]
	global_load_dword v74, v15, s[98:99]
	global_load_dword v67, v19, s[98:99] offset:2048
	global_load_dword v75, v15, s[98:99] offset:2048
	global_load_dword v68, v20, s[98:99]
	global_load_dword v76, v16, s[98:99]
	global_load_dword v69, v20, s[98:99] offset:2048
	global_load_dword v77, v16, s[98:99] offset:2048
	global_load_dword v70, v21, s[98:99]
	global_load_dword v78, v17, s[98:99]
	global_load_dword v71, v21, s[98:99] offset:2048
	global_load_dword v79, v17, s[98:99] offset:2048
	s_waitcnt vmcnt(16)
	v_add_f32_e32 v80, 1.0, v48
	v_add_f32_e32 v80, v80, v40
	v_mul_f32_e32 v80, v24, v80
	v_add_f32_e32 v81, v56, v32
	ds_write_b32 v183, v80 offset:32768
	ds_write_b32 v22, v81 offset:32768
	v_add_f32_e32 v80, 1.0, v49
	v_add_f32_e32 v80, v80, v41
	v_mul_f32_e32 v80, v25, v80
	v_add_f32_e32 v81, v57, v33
	ds_write_b32 v183, v80 offset:34816
	ds_write_b32 v22, v81 offset:34816
	v_add_f32_e32 v80, 1.0, v50
	v_add_f32_e32 v80, v80, v42
	v_mul_f32_e32 v80, v26, v80
	v_add_f32_e32 v81, v58, v34
	ds_write_b32 v183, v80 offset:36864
	ds_write_b32 v22, v81 offset:36864
	v_add_f32_e32 v80, 1.0, v51
	v_add_f32_e32 v80, v80, v43
	v_mul_f32_e32 v80, v27, v80
	v_add_f32_e32 v81, v59, v35
	ds_write_b32 v183, v80 offset:38912
	ds_write_b32 v22, v81 offset:38912
	v_add_f32_e32 v80, 1.0, v52
	v_add_f32_e32 v80, v80, v44
	v_mul_f32_e32 v80, v28, v80
	v_add_f32_e32 v81, v60, v36
	ds_write_b32 v183, v80 offset:40960
	ds_write_b32 v22, v81 offset:40960
	v_add_f32_e32 v80, 1.0, v53
	v_add_f32_e32 v80, v80, v45
	v_mul_f32_e32 v80, v29, v80
	v_add_f32_e32 v81, v61, v37
	ds_write_b32 v183, v80 offset:43008
	ds_write_b32 v22, v81 offset:43008
	v_add_f32_e32 v80, 1.0, v54
	v_add_f32_e32 v80, v80, v46
	v_mul_f32_e32 v80, v30, v80
	v_add_f32_e32 v81, v62, v38
	ds_write_b32 v183, v80 offset:45056
	ds_write_b32 v22, v81 offset:45056
	v_add_f32_e32 v80, 1.0, v55
	v_add_f32_e32 v80, v80, v47
	v_mul_f32_e32 v80, v31, v80
	v_add_f32_e32 v81, v63, v39
	ds_write_b32 v183, v80 offset:47104
	ds_write_b32 v22, v81 offset:47104
	s_waitcnt vmcnt(0)
	v_add_f32_e32 v80, 1.0, v64
	v_add_f32_e32 v80, v80, v40
	v_mul_f32_e32 v80, v24, v80
	v_add_f32_e32 v81, v72, v32
	ds_write_b32 v183, v80 offset:49152
	ds_write_b32 v22, v81 offset:49152
	v_add_f32_e32 v80, 1.0, v65
	v_add_f32_e32 v80, v80, v41
	v_mul_f32_e32 v80, v25, v80
	v_add_f32_e32 v81, v73, v33
	ds_write_b32 v183, v80 offset:51200
	ds_write_b32 v22, v81 offset:51200
	v_add_f32_e32 v80, 1.0, v66
	v_add_f32_e32 v80, v80, v42
	v_mul_f32_e32 v80, v26, v80
	v_add_f32_e32 v81, v74, v34
	ds_write_b32 v183, v80 offset:53248
	ds_write_b32 v22, v81 offset:53248
	v_add_f32_e32 v80, 1.0, v67
	v_add_f32_e32 v80, v80, v43
	v_mul_f32_e32 v80, v27, v80
	v_add_f32_e32 v81, v75, v35
	ds_write_b32 v183, v80 offset:55296
	ds_write_b32 v22, v81 offset:55296
	v_add_f32_e32 v80, 1.0, v68
	v_add_f32_e32 v80, v80, v44
	v_mul_f32_e32 v80, v28, v80
	v_add_f32_e32 v81, v76, v36
	ds_write_b32 v183, v80 offset:57344
	ds_write_b32 v22, v81 offset:57344
	v_add_f32_e32 v80, 1.0, v69
	v_add_f32_e32 v80, v80, v45
	v_mul_f32_e32 v80, v29, v80
	v_add_f32_e32 v81, v77, v37
	ds_write_b32 v183, v80 offset:59392
	ds_write_b32 v22, v81 offset:59392
	v_add_f32_e32 v80, 1.0, v70
	v_add_f32_e32 v80, v80, v46
	v_mul_f32_e32 v80, v30, v80
	v_add_f32_e32 v81, v78, v38
	ds_write_b32 v183, v80 offset:61440
	ds_write_b32 v22, v81 offset:61440
	v_add_f32_e32 v80, 1.0, v71
	v_add_f32_e32 v80, v80, v47
	v_mul_f32_e32 v80, v31, v80
	v_add_f32_e32 v81, v79, v39
	ds_write_b32 v183, v80 offset:63488
	ds_write_b32 v22, v81 offset:63488
	s_or_b64 exec, exec, s[6:7]
	s_cmpk_gt_i32 s4, 0x3fff
	s_waitcnt lgkmcnt(0)
	s_barrier
	s_cbranch_scc1 .LBB0_847
	s_add_u32 s8, s68, 0x55000000
	s_addc_u32 s9, s69, 0
	s_ashr_i32 s5, s4, 31
	s_lshl_b64 s[10:11], s[4:5], 13
	s_add_u32 s6, s8, s10
	s_addc_u32 s7, s9, s11
	v_lshlrev_b32_e32 v66, 4, v163
	v_mov_b32_e32 v67, 0
	v_lshl_add_u64 v[18:19], s[6:7], 0, v[66:67]
	s_movk_i32 s5, 0x1000
	v_add_co_u32_e32 v34, vcc, s5, v18
	global_load_dwordx4 v[2:5], v66, s[6:7]
	global_load_dwordx4 v[6:9], v66, s[6:7] offset:1024
	global_load_dwordx4 v[10:13], v66, s[6:7] offset:2048
	global_load_dwordx4 v[14:17], v66, s[6:7] offset:3072
	v_addc_co_u32_e32 v35, vcc, 0, v19, vcc
	global_load_dwordx4 v[18:21], v[34:35], off
	global_load_dwordx4 v[22:25], v[34:35], off offset:1024
	global_load_dwordx4 v[26:29], v[34:35], off offset:2048
	global_load_dwordx4 v[30:33], v[34:35], off offset:3072
	v_mbcnt_lo_u32_b32 v34, -1, 0
	v_mbcnt_hi_u32_b32 v34, -1, v34
	v_and_b32_e32 v35, 64, v34
	v_add_u32_e32 v35, 64, v35
	v_xor_b32_e32 v36, 1, v34
	v_cmp_lt_i32_e32 vcc, v36, v35
	s_lshl_b32 s6, s33, 4
	v_lshl_add_u64 v[68:69], s[8:9], 0, v[66:67]
	v_cndmask_b32_e32 v36, v34, v36, vcc
	v_lshlrev_b32_e32 v120, 2, v36
	v_xor_b32_e32 v36, 2, v34
	v_cmp_lt_i32_e32 vcc, v36, v35
	s_add_u32 s8, s68, s10
	v_readlane_b32 s5, v254, 23
	v_cndmask_b32_e32 v36, v34, v36, vcc
	v_lshlrev_b32_e32 v121, 2, v36
	v_xor_b32_e32 v36, 4, v34
	v_cmp_lt_i32_e32 vcc, v36, v35
	s_addc_u32 s9, s69, s11
	s_add_i32 s5, s5, s18
	v_cndmask_b32_e32 v36, v34, v36, vcc
	v_lshlrev_b32_e32 v122, 2, v36
	v_xor_b32_e32 v36, 8, v34
	v_cmp_lt_i32_e32 vcc, v36, v35
	s_add_i32 s12, s5, s12
	s_ashr_i32 s7, s6, 31
	v_cndmask_b32_e32 v36, v34, v36, vcc
	v_lshlrev_b32_e32 v123, 2, v36
	v_xor_b32_e32 v36, 16, v34
	v_cmp_lt_i32_e32 vcc, v36, v35
	s_ashr_i32 s13, s12, 31
	s_lshl_b64 s[10:11], s[6:7], 13
	v_cndmask_b32_e32 v36, v34, v36, vcc
	v_lshlrev_b32_e32 v124, 2, v36
	v_xor_b32_e32 v36, 32, v34
	v_cmp_lt_i32_e32 vcc, v36, v35
	s_lshl_b64 s[12:13], s[12:13], 13
	s_add_u32 s12, s68, s12
	v_cndmask_b32_e32 v34, v34, v36, vcc
	v_lshlrev_b32_e32 v1, 3, v163
	v_lshlrev_b32_e32 v125, 2, v34
	s_addc_u32 s13, s69, s13
	v_mov_b32_e32 v126, 0x358637bd
	s_mov_b32 s7, 0x800000
	s_mov_b32 s19, 0x11000000
	s_mov_b32 s20, 0x11001000
	s_branch .LBB0_841
